# P16: workgroups idle in the half-empty last round touch their XCD's operand lines for that round (paced, K order) so the working half's LDS-DMA hits L2
# speedup vs baseline: 1.0027x; 1.0027x over previous
.LBB0_1981:
	s_waitcnt vmcnt(0)
	s_barrier
	s_cmpk_lt_u32 s2, 0x80
	s_cbranch_scc1 .Lpf16_skip
	s_and_b32 s12, s2, 7
	s_lshr_b32 s13, s2, 3
	s_and_b32 s14, s13, 7
	s_lshl_b32 s14, s14, 7
	v_lshrrev_b32_e32 v222, 6, v185
	v_lshrrev_b32_e32 v223, 2, v184
	v_lshl_add_u32 v222, v222, 4, v223
	v_add_u32_e32 v222, s14, v222
	s_bitcmp1_b32 s13, 3
	s_cbranch_scc1 .Lpf16_B
	s_lshl_b32 s15, s12, 3
	s_add_u32 s15, s15, 4
	s_lshl_b32 s15, s15, 8
	s_mov_b64 s[16:17], s[82:83]
	s_branch .Lpf16_go
.Lpf16_B:
	s_movk_i32 s15, 0x1200
	s_add_u32 s16, s76, 0x400000
	s_addc_u32 s17, s77, 0
.Lpf16_go:
	v_add_u32_e32 v222, s15, v222
	v_lshlrev_b32_e32 v222, 11, v222
	v_and_b32_e32 v223, 3, v184
	v_lshl_add_u32 v222, v223, 7, v222
	global_load_dword v224, v222, s[16:17]
	s_sleep 64
	global_load_dword v225, v222, s[16:17] offset:512
	s_sleep 64
	global_load_dword v226, v222, s[16:17] offset:1024
	s_sleep 64
	global_load_dword v227, v222, s[16:17] offset:1536
.Lpf16_skip:
.LBB0_1982:
	s_cmp_gt_i32 s79, 17
	s_cselect_b64 s[4:5], -1, 0
	s_and_b64 s[0:1], s[0:1], s[4:5]
	s_andn2_b64 vcc, exec, s[0:1]
	s_cbranch_vccnz .LBB0_2036
	s_waitcnt vmcnt(0) lgkmcnt(0)
	s_barrier
	v_readlane_b32 s12, v243, 0
	s_cmp_eq_u32 s12, 0
	s_cbranch_scc1 .Lfb_14
	v_readlane_b32 s21, v243, 1
	s_add_u32 s21, s21, 1
	v_writelane_b32 v243, s21, 1
	v_readlane_b32 s12, v242, 1
	v_readlane_b32 s13, v242, 2
	s_mov_b64 s[14:15], exec
	s_and_b64 s[12:13], s[14:15], s[12:13]
	s_mov_b64 exec, s[12:13]
	s_cbranch_execz .Llb_done_14
	s_and_b32 s16, s2, 7
	s_lshl_b32 s16, s16, 6
	s_add_u32 s16, s76, s16
	s_addc_u32 s17, s77, 0
	v_mov_b32_e32 v1, 0x3000
	v_mov_b32_e32 v4, 1
	global_atomic_add v1, v4, s[16:17] offset:2112
	buffer_inv sc1
	s_lshl_b32 s23, s21, 5
